# seam: followers poll cross-XCD generation word directly (flat release), plus wave-1 L1 invalidate
# speedup vs baseline: 1.0034x; 1.0025x over previous
; __device__ __forceinline__ unsigned xb_ld(unsigned* p)              { return __hip_atomic_load(p, __ATOMIC_RELAXED, __HIP_MEMORY_SCOPE_AGENT); }
; __device__ __forceinline__ unsigned xb_add(unsigned* p, unsigned v) { return __hip_atomic_fetch_add(p, v, __ATOMIC_RELAXED, __HIP_MEMORY_SCOPE_AGENT); }
; #define XB_SPIN(cond, bar) do { unsigned _sp = 0; while (cond) { __builtin_amdgcn_s_sleep(1); \
;     if ((++_sp & 255u) == 0u) { if (xb_ld(&(bar)[XB_TMO])) break; if (_sp > XB_SPIN_CAP) { atomicAdd(&(bar)[XB_TMO], 1u); break; } } } } while (0)
; __device__ __forceinline__ void xcd_barrier(const XcdBarrier& b) {
;     ...
;         const unsigned old = xb_add(&bar[XB_XSUB(b.x)], 1u);
;         const unsigned gen = old / nloc;
;         if (old + 1u == (gen + 1u) * nloc) {
;             __builtin_amdgcn_fence(__ATOMIC_RELEASE, "agent");
;             asm volatile("s_waitcnt vmcnt(0)" ::: "memory");
;             const unsigned og = xb_add(&bar[XB_TOP], 1u);
;             const unsigned tg = og / nx;
;             if (og + 1u == (tg + 1u) * nx) xb_add(&bar[XB_TOPGEN], 1u);
;             else XB_SPIN(xb_ld(&bar[XB_TOPGEN]) == tg, bar);
;             __builtin_amdgcn_fence(__ATOMIC_ACQUIRE, "agent");
;             xb_add(&bar[XB_XGEN(b.x)], 1u);
;             asm volatile("s_waitcnt vmcnt(0)" ::: "memory");
;         } else {
;             XB_SPIN(xb_ld(&bar[XB_XGEN(b.x)]) == gen, bar);
.LBB0_307:
	v_readlane_b32 s4, v254, 16
	s_lshl_b32 s4, s4, 8
	v_readlane_b32 s10, v254, 12
	v_readlane_b32 s11, v254, 13
	s_add_u32 s4, s10, s4
	s_addc_u32 s5, s11, 0
	v_mov_b32_e32 v3, 0x1000
	v_mov_b32_e32 v5, 1
	global_atomic_add v5, v3, v5, s[4:5] offset:1024 sc0
	v_cvt_f32_u32_e32 v3, v4
	v_sub_u32_e32 v6, 0, v4
	v_rcp_iflag_f32_e32 v3, v3
	s_nop 0
	v_mul_f32_e32 v3, 0x4f7ffffe, v3
	v_cvt_u32_f32_e32 v3, v3
	v_mul_lo_u32 v6, v6, v3
	v_mul_hi_u32 v6, v3, v6
	v_add_u32_e32 v3, v3, v6
	s_waitcnt vmcnt(0)
	v_mul_hi_u32 v3, v5, v3
	v_mul_lo_u32 v6, v3, v4
	v_sub_u32_e32 v6, v5, v6
	v_add_u32_e32 v7, 1, v3
	v_cmp_ge_u32_e32 vcc, v6, v4
	v_add_u32_e32 v5, 1, v5
	s_nop 0
	v_cndmask_b32_e32 v3, v3, v7, vcc
	v_sub_u32_e32 v7, v6, v4
	v_cndmask_b32_e32 v6, v6, v7, vcc
	v_add_u32_e32 v7, 1, v3
	v_cmp_ge_u32_e32 vcc, v6, v4
	s_nop 1
	v_cndmask_b32_e32 v3, v3, v7, vcc
	v_mul_lo_u32 v6, v4, v3
	v_add_u32_e32 v4, v6, v4
	v_cmp_ne_u32_e32 vcc, v5, v4
	s_and_saveexec_b64 s[10:11], vcc
	s_xor_b64 s[10:11], exec, s[10:11]
	s_cbranch_execz .LBB0_321
	s_waitcnt lgkmcnt(0)
	s_add_u32 s18, s84, 0x33500
	s_addc_u32 s19, s85, 0
	v_mov_b32_e32 v2, 0
	global_load_dword v2, v2, s[18:19] sc1
	s_waitcnt vmcnt(0)
	v_cmp_eq_u32_e32 vcc, v2, v3
	s_and_saveexec_b64 s[14:15], vcc
	s_cbranch_execz .LBB0_320
	s_add_u32 s16, s84, 0x30200
	s_addc_u32 s17, s85, 0
	s_mov_b32 s30, 1
	s_mov_b64 s[20:21], 0
	v_mov_b32_e32 v2, 0
	s_branch .LBB0_311

; __device__ __forceinline__ unsigned xb_ld(unsigned* p)              { return __hip_atomic_load(p, __ATOMIC_RELAXED, __HIP_MEMORY_SCOPE_AGENT); }
; __device__ __forceinline__ unsigned xb_add(unsigned* p, unsigned v) { return __hip_atomic_fetch_add(p, v, __ATOMIC_RELAXED, __HIP_MEMORY_SCOPE_AGENT); }
; #define XB_SPIN(cond, bar) do { unsigned _sp = 0; while (cond) { __builtin_amdgcn_s_sleep(1); \
;     if ((++_sp & 255u) == 0u) { if (xb_ld(&(bar)[XB_TMO])) break; if (_sp > XB_SPIN_CAP) { atomicAdd(&(bar)[XB_TMO], 1u); break; } } } } while (0)
; __device__ __forceinline__ void xcd_barrier(const XcdBarrier& b) {
;     ...
;         const unsigned old = xb_add(&bar[XB_XSUB(b.x)], 1u);
;         const unsigned gen = old / nloc;
;         if (old + 1u == (gen + 1u) * nloc) {
;             __builtin_amdgcn_fence(__ATOMIC_RELEASE, "agent");
;             asm volatile("s_waitcnt vmcnt(0)" ::: "memory");
;             const unsigned og = xb_add(&bar[XB_TOP], 1u);
;             const unsigned tg = og / nx;
;             if (og + 1u == (tg + 1u) * nx) xb_add(&bar[XB_TOPGEN], 1u);
;             else XB_SPIN(xb_ld(&bar[XB_TOPGEN]) == tg, bar);
;             __builtin_amdgcn_fence(__ATOMIC_ACQUIRE, "agent");
;             xb_add(&bar[XB_XGEN(b.x)], 1u);
;             asm volatile("s_waitcnt vmcnt(0)" ::: "memory");
;         } else {
;             XB_SPIN(xb_ld(&bar[XB_XGEN(b.x)]) == gen, bar);
.LBB0_538:
	v_readlane_b32 s4, v254, 16
	s_lshl_b32 s4, s4, 8
	v_readlane_b32 s12, v254, 12
	v_readlane_b32 s13, v254, 13
	s_add_u32 s4, s12, s4
	s_addc_u32 s5, s13, 0
	v_mov_b32_e32 v3, 0x1000
	v_mov_b32_e32 v5, 1
	global_atomic_add v5, v3, v5, s[4:5] offset:1024 sc0
	v_cvt_f32_u32_e32 v3, v4
	v_sub_u32_e32 v6, 0, v4
	v_rcp_iflag_f32_e32 v3, v3
	s_nop 0
	v_mul_f32_e32 v3, 0x4f7ffffe, v3
	v_cvt_u32_f32_e32 v3, v3
	v_mul_lo_u32 v6, v6, v3
	v_mul_hi_u32 v6, v3, v6
	v_add_u32_e32 v3, v3, v6
	s_waitcnt vmcnt(0)
	v_mul_hi_u32 v3, v5, v3
	v_mul_lo_u32 v6, v3, v4
	v_sub_u32_e32 v6, v5, v6
	v_add_u32_e32 v7, 1, v3
	v_cmp_ge_u32_e32 vcc, v6, v4
	v_add_u32_e32 v5, 1, v5
	s_nop 0
	v_cndmask_b32_e32 v3, v3, v7, vcc
	v_sub_u32_e32 v7, v6, v4
	v_cndmask_b32_e32 v6, v6, v7, vcc
	v_add_u32_e32 v7, 1, v3
	v_cmp_ge_u32_e32 vcc, v6, v4
	s_nop 1
	v_cndmask_b32_e32 v3, v3, v7, vcc
	v_mul_lo_u32 v6, v4, v3
	v_add_u32_e32 v4, v6, v4
	v_cmp_ne_u32_e32 vcc, v5, v4
	s_and_saveexec_b64 s[12:13], vcc
	s_xor_b64 s[12:13], exec, s[12:13]
	s_cbranch_execz .LBB0_552
	s_waitcnt lgkmcnt(0)
	s_add_u32 s18, s84, 0x33500
	s_addc_u32 s19, s85, 0
	v_mov_b32_e32 v2, 0
	global_load_dword v2, v2, s[18:19] sc1
	s_waitcnt vmcnt(0)
	v_cmp_eq_u32_e32 vcc, v2, v3
	s_and_saveexec_b64 s[14:15], vcc
	s_cbranch_execz .LBB0_551
	s_add_u32 s16, s84, 0x30200
	s_addc_u32 s17, s85, 0
	s_mov_b32 s30, 1
	s_mov_b64 s[20:21], 0
	v_mov_b32_e32 v2, 0
	s_branch .LBB0_542

; __device__ __forceinline__ unsigned xb_ld(unsigned* p)              { return __hip_atomic_load(p, __ATOMIC_RELAXED, __HIP_MEMORY_SCOPE_AGENT); }
; __device__ __forceinline__ unsigned xb_add(unsigned* p, unsigned v) { return __hip_atomic_fetch_add(p, v, __ATOMIC_RELAXED, __HIP_MEMORY_SCOPE_AGENT); }
; #define XB_SPIN(cond, bar) do { unsigned _sp = 0; while (cond) { __builtin_amdgcn_s_sleep(1); \
;     if ((++_sp & 255u) == 0u) { if (xb_ld(&(bar)[XB_TMO])) break; if (_sp > XB_SPIN_CAP) { atomicAdd(&(bar)[XB_TMO], 1u); break; } } } } while (0)
; __device__ __forceinline__ void xcd_barrier(const XcdBarrier& b) {
;     ...
;         const unsigned old = xb_add(&bar[XB_XSUB(b.x)], 1u);
;         const unsigned gen = old / nloc;
;         if (old + 1u == (gen + 1u) * nloc) {
;             __builtin_amdgcn_fence(__ATOMIC_RELEASE, "agent");
;             asm volatile("s_waitcnt vmcnt(0)" ::: "memory");
;             const unsigned og = xb_add(&bar[XB_TOP], 1u);
;             const unsigned tg = og / nx;
;             if (og + 1u == (tg + 1u) * nx) xb_add(&bar[XB_TOPGEN], 1u);
;             else XB_SPIN(xb_ld(&bar[XB_TOPGEN]) == tg, bar);
;             __builtin_amdgcn_fence(__ATOMIC_ACQUIRE, "agent");
;             xb_add(&bar[XB_XGEN(b.x)], 1u);
;             asm volatile("s_waitcnt vmcnt(0)" ::: "memory");
;         } else {
;             XB_SPIN(xb_ld(&bar[XB_XGEN(b.x)]) == gen, bar);
.LBB0_649:
	v_readlane_b32 s4, v254, 16
	s_lshl_b32 s4, s4, 8
	v_readlane_b32 s12, v254, 12
	v_readlane_b32 s13, v254, 13
	s_add_u32 s4, s12, s4
	s_addc_u32 s5, s13, 0
	v_mov_b32_e32 v3, 0x1000
	v_mov_b32_e32 v5, 1
	global_atomic_add v5, v3, v5, s[4:5] offset:1024 sc0
	v_cvt_f32_u32_e32 v3, v4
	v_sub_u32_e32 v6, 0, v4
	v_rcp_iflag_f32_e32 v3, v3
	s_nop 0
	v_mul_f32_e32 v3, 0x4f7ffffe, v3
	v_cvt_u32_f32_e32 v3, v3
	v_mul_lo_u32 v6, v6, v3
	v_mul_hi_u32 v6, v3, v6
	v_add_u32_e32 v3, v3, v6
	s_waitcnt vmcnt(0)
	v_mul_hi_u32 v3, v5, v3
	v_mul_lo_u32 v6, v3, v4
	v_sub_u32_e32 v6, v5, v6
	v_add_u32_e32 v7, 1, v3
	v_cmp_ge_u32_e32 vcc, v6, v4
	v_add_u32_e32 v5, 1, v5
	s_nop 0
	v_cndmask_b32_e32 v3, v3, v7, vcc
	v_sub_u32_e32 v7, v6, v4
	v_cndmask_b32_e32 v6, v6, v7, vcc
	v_add_u32_e32 v7, 1, v3
	v_cmp_ge_u32_e32 vcc, v6, v4
	s_nop 1
	v_cndmask_b32_e32 v3, v3, v7, vcc
	v_mul_lo_u32 v6, v4, v3
	v_add_u32_e32 v4, v6, v4
	v_cmp_ne_u32_e32 vcc, v5, v4
	s_and_saveexec_b64 s[12:13], vcc
	s_xor_b64 s[12:13], exec, s[12:13]
	s_cbranch_execz .LBB0_663
	s_waitcnt lgkmcnt(0)
	s_add_u32 s20, s84, 0x33500
	s_addc_u32 s21, s85, 0
	v_mov_b32_e32 v2, 0
	global_load_dword v2, v2, s[20:21] sc1
	s_waitcnt vmcnt(0)
	v_cmp_eq_u32_e32 vcc, v2, v3
	s_and_saveexec_b64 s[14:15], vcc
	s_cbranch_execz .LBB0_662
	s_add_u32 s16, s84, 0x30200
	s_addc_u32 s17, s85, 0
	s_mov_b32 s33, 1
	s_mov_b64 s[22:23], 0
	v_mov_b32_e32 v2, 0
	s_branch .LBB0_653

; __device__ __forceinline__ unsigned xb_ld(unsigned* p)              { return __hip_atomic_load(p, __ATOMIC_RELAXED, __HIP_MEMORY_SCOPE_AGENT); }
; __device__ __forceinline__ unsigned xb_add(unsigned* p, unsigned v) { return __hip_atomic_fetch_add(p, v, __ATOMIC_RELAXED, __HIP_MEMORY_SCOPE_AGENT); }
; #define XB_SPIN(cond, bar) do { unsigned _sp = 0; while (cond) { __builtin_amdgcn_s_sleep(1); \
;     if ((++_sp & 255u) == 0u) { if (xb_ld(&(bar)[XB_TMO])) break; if (_sp > XB_SPIN_CAP) { atomicAdd(&(bar)[XB_TMO], 1u); break; } } } } while (0)
; __device__ __forceinline__ void xcd_barrier(const XcdBarrier& b) {
;     ...
;         const unsigned old = xb_add(&bar[XB_XSUB(b.x)], 1u);
;         const unsigned gen = old / nloc;
;         if (old + 1u == (gen + 1u) * nloc) {
;             __builtin_amdgcn_fence(__ATOMIC_RELEASE, "agent");
;             asm volatile("s_waitcnt vmcnt(0)" ::: "memory");
;             const unsigned og = xb_add(&bar[XB_TOP], 1u);
;             const unsigned tg = og / nx;
;             if (og + 1u == (tg + 1u) * nx) xb_add(&bar[XB_TOPGEN], 1u);
;             else XB_SPIN(xb_ld(&bar[XB_TOPGEN]) == tg, bar);
;             __builtin_amdgcn_fence(__ATOMIC_ACQUIRE, "agent");
;             xb_add(&bar[XB_XGEN(b.x)], 1u);
;             asm volatile("s_waitcnt vmcnt(0)" ::: "memory");
;         } else {
;             XB_SPIN(xb_ld(&bar[XB_XGEN(b.x)]) == gen, bar);
.LBB0_974:
	v_readlane_b32 s4, v254, 16
	s_lshl_b32 s4, s4, 8
	v_readlane_b32 s6, v254, 12
	v_readlane_b32 s7, v254, 13
	s_add_u32 s4, s6, s4
	s_addc_u32 s5, s7, 0
	v_mov_b32_e32 v3, 0x1000
	v_mov_b32_e32 v5, 1
	global_atomic_add v5, v3, v5, s[4:5] offset:1024 sc0
	v_cvt_f32_u32_e32 v3, v4
	v_sub_u32_e32 v6, 0, v4
	v_rcp_iflag_f32_e32 v3, v3
	s_nop 0
	v_mul_f32_e32 v3, 0x4f7ffffe, v3
	v_cvt_u32_f32_e32 v3, v3
	v_mul_lo_u32 v6, v6, v3
	v_mul_hi_u32 v6, v3, v6
	v_add_u32_e32 v3, v3, v6
	s_waitcnt vmcnt(0)
	v_mul_hi_u32 v3, v5, v3
	v_mul_lo_u32 v6, v3, v4
	v_sub_u32_e32 v6, v5, v6
	v_add_u32_e32 v7, 1, v3
	v_cmp_ge_u32_e32 vcc, v6, v4
	v_add_u32_e32 v5, 1, v5
	s_nop 0
	v_cndmask_b32_e32 v3, v3, v7, vcc
	v_sub_u32_e32 v7, v6, v4
	v_cndmask_b32_e32 v6, v6, v7, vcc
	v_add_u32_e32 v7, 1, v3
	v_cmp_ge_u32_e32 vcc, v6, v4
	s_nop 1
	v_cndmask_b32_e32 v3, v3, v7, vcc
	v_mul_lo_u32 v6, v4, v3
	v_add_u32_e32 v4, v6, v4
	v_cmp_ne_u32_e32 vcc, v5, v4
	s_and_saveexec_b64 s[6:7], vcc
	s_xor_b64 s[6:7], exec, s[6:7]
	s_cbranch_execz .LBB0_988
	s_waitcnt lgkmcnt(0)
	s_add_u32 s14, s84, 0x33500
	s_addc_u32 s15, s85, 0
	v_mov_b32_e32 v2, 0
	global_load_dword v2, v2, s[14:15] sc1
	s_waitcnt vmcnt(0)
	v_cmp_eq_u32_e32 vcc, v2, v3
	s_and_saveexec_b64 s[8:9], vcc
	s_cbranch_execz .LBB0_987
	s_add_u32 s10, s84, 0x30200
	s_addc_u32 s11, s85, 0
	s_mov_b32 s26, 1
	s_mov_b64 s[16:17], 0
	v_mov_b32_e32 v2, 0
	s_branch .LBB0_978

; __device__ __forceinline__ unsigned xb_ld(unsigned* p)              { return __hip_atomic_load(p, __ATOMIC_RELAXED, __HIP_MEMORY_SCOPE_AGENT); }
; __device__ __forceinline__ unsigned xb_add(unsigned* p, unsigned v) { return __hip_atomic_fetch_add(p, v, __ATOMIC_RELAXED, __HIP_MEMORY_SCOPE_AGENT); }
; #define XB_SPIN(cond, bar) do { unsigned _sp = 0; while (cond) { __builtin_amdgcn_s_sleep(1); \
;     if ((++_sp & 255u) == 0u) { if (xb_ld(&(bar)[XB_TMO])) break; if (_sp > XB_SPIN_CAP) { atomicAdd(&(bar)[XB_TMO], 1u); break; } } } } while (0)
; __device__ __forceinline__ void xcd_barrier(const XcdBarrier& b) {
;     ...
;         const unsigned old = xb_add(&bar[XB_XSUB(b.x)], 1u);
;         const unsigned gen = old / nloc;
;         if (old + 1u == (gen + 1u) * nloc) {
;             __builtin_amdgcn_fence(__ATOMIC_RELEASE, "agent");
;             asm volatile("s_waitcnt vmcnt(0)" ::: "memory");
;             const unsigned og = xb_add(&bar[XB_TOP], 1u);
;             const unsigned tg = og / nx;
;             if (og + 1u == (tg + 1u) * nx) xb_add(&bar[XB_TOPGEN], 1u);
;             else XB_SPIN(xb_ld(&bar[XB_TOPGEN]) == tg, bar);
;             __builtin_amdgcn_fence(__ATOMIC_ACQUIRE, "agent");
;             xb_add(&bar[XB_XGEN(b.x)], 1u);
;             asm volatile("s_waitcnt vmcnt(0)" ::: "memory");
;         } else {
;             XB_SPIN(xb_ld(&bar[XB_XGEN(b.x)]) == gen, bar);
.LBB0_1101:
	v_readlane_b32 s4, v254, 16
	s_lshl_b32 s4, s4, 8
	v_readlane_b32 s6, v254, 12
	v_readlane_b32 s7, v254, 13
	s_add_u32 s4, s6, s4
	s_addc_u32 s5, s7, 0
	v_mov_b32_e32 v3, 0x1000
	v_mov_b32_e32 v5, 1
	global_atomic_add v5, v3, v5, s[4:5] offset:1024 sc0
	v_cvt_f32_u32_e32 v3, v4
	v_sub_u32_e32 v6, 0, v4
	v_rcp_iflag_f32_e32 v3, v3
	s_nop 0
	v_mul_f32_e32 v3, 0x4f7ffffe, v3
	v_cvt_u32_f32_e32 v3, v3
	v_mul_lo_u32 v6, v6, v3
	v_mul_hi_u32 v6, v3, v6
	v_add_u32_e32 v3, v3, v6
	s_waitcnt vmcnt(0)
	v_mul_hi_u32 v3, v5, v3
	v_mul_lo_u32 v6, v3, v4
	v_sub_u32_e32 v6, v5, v6
	v_add_u32_e32 v7, 1, v3
	v_cmp_ge_u32_e32 vcc, v6, v4
	v_add_u32_e32 v5, 1, v5
	s_nop 0
	v_cndmask_b32_e32 v3, v3, v7, vcc
	v_sub_u32_e32 v7, v6, v4
	v_cndmask_b32_e32 v6, v6, v7, vcc
	v_add_u32_e32 v7, 1, v3
	v_cmp_ge_u32_e32 vcc, v6, v4
	s_nop 1
	v_cndmask_b32_e32 v3, v3, v7, vcc
	v_mul_lo_u32 v6, v4, v3
	v_add_u32_e32 v4, v6, v4
	v_cmp_ne_u32_e32 vcc, v5, v4
	s_and_saveexec_b64 s[6:7], vcc
	s_xor_b64 s[6:7], exec, s[6:7]
	s_cbranch_execz .LBB0_1115
	s_waitcnt lgkmcnt(0)
	s_add_u32 s12, s84, 0x33500
	s_addc_u32 s13, s85, 0
	v_mov_b32_e32 v2, 0
	global_load_dword v2, v2, s[12:13] sc1
	s_waitcnt vmcnt(0)
	v_cmp_eq_u32_e32 vcc, v2, v3
	s_and_saveexec_b64 s[8:9], vcc
	s_cbranch_execz .LBB0_1114
	s_add_u32 s10, s84, 0x30200
	s_addc_u32 s11, s85, 0
	s_mov_b32 s24, 1
	s_mov_b64 s[14:15], 0
	v_mov_b32_e32 v2, 0
	s_branch .LBB0_1105

; __device__ __forceinline__ unsigned xb_ld(unsigned* p)              { return __hip_atomic_load(p, __ATOMIC_RELAXED, __HIP_MEMORY_SCOPE_AGENT); }
; __device__ __forceinline__ unsigned xb_add(unsigned* p, unsigned v) { return __hip_atomic_fetch_add(p, v, __ATOMIC_RELAXED, __HIP_MEMORY_SCOPE_AGENT); }
; #define XB_SPIN(cond, bar) do { unsigned _sp = 0; while (cond) { __builtin_amdgcn_s_sleep(1); \
;     if ((++_sp & 255u) == 0u) { if (xb_ld(&(bar)[XB_TMO])) break; if (_sp > XB_SPIN_CAP) { atomicAdd(&(bar)[XB_TMO], 1u); break; } } } } while (0)
; __device__ __forceinline__ void xcd_barrier(const XcdBarrier& b) {
;     ...
;         const unsigned old = xb_add(&bar[XB_XSUB(b.x)], 1u);
;         const unsigned gen = old / nloc;
;         if (old + 1u == (gen + 1u) * nloc) {
;             __builtin_amdgcn_fence(__ATOMIC_RELEASE, "agent");
;             asm volatile("s_waitcnt vmcnt(0)" ::: "memory");
;             const unsigned og = xb_add(&bar[XB_TOP], 1u);
;             const unsigned tg = og / nx;
;             if (og + 1u == (tg + 1u) * nx) xb_add(&bar[XB_TOPGEN], 1u);
;             else XB_SPIN(xb_ld(&bar[XB_TOPGEN]) == tg, bar);
;             __builtin_amdgcn_fence(__ATOMIC_ACQUIRE, "agent");
;             xb_add(&bar[XB_XGEN(b.x)], 1u);
;             asm volatile("s_waitcnt vmcnt(0)" ::: "memory");
;         } else {
;             XB_SPIN(xb_ld(&bar[XB_XGEN(b.x)]) == gen, bar);
.LBB0_1371:
	v_readlane_b32 s8, v254, 16
	s_lshl_b32 s8, s8, 8
	v_readlane_b32 s10, v254, 12
	v_readlane_b32 s11, v254, 13
	s_add_u32 s8, s10, s8
	s_addc_u32 s9, s11, 0
	v_mov_b32_e32 v3, 0x1000
	v_mov_b32_e32 v5, 1
	global_atomic_add v5, v3, v5, s[8:9] offset:1024 sc0
	v_cvt_f32_u32_e32 v3, v4
	v_sub_u32_e32 v6, 0, v4
	v_rcp_iflag_f32_e32 v3, v3
	s_nop 0
	v_mul_f32_e32 v3, 0x4f7ffffe, v3
	v_cvt_u32_f32_e32 v3, v3
	v_mul_lo_u32 v6, v6, v3
	v_mul_hi_u32 v6, v3, v6
	v_add_u32_e32 v3, v3, v6
	s_waitcnt vmcnt(0)
	v_mul_hi_u32 v3, v5, v3
	v_mul_lo_u32 v6, v3, v4
	v_sub_u32_e32 v6, v5, v6
	v_add_u32_e32 v7, 1, v3
	v_cmp_ge_u32_e32 vcc, v6, v4
	v_add_u32_e32 v5, 1, v5
	s_nop 0
	v_cndmask_b32_e32 v3, v3, v7, vcc
	v_sub_u32_e32 v7, v6, v4
	v_cndmask_b32_e32 v6, v6, v7, vcc
	v_add_u32_e32 v7, 1, v3
	v_cmp_ge_u32_e32 vcc, v6, v4
	s_nop 1
	v_cndmask_b32_e32 v3, v3, v7, vcc
	v_mul_lo_u32 v6, v4, v3
	v_add_u32_e32 v4, v6, v4
	v_cmp_ne_u32_e32 vcc, v5, v4
	s_and_saveexec_b64 s[10:11], vcc
	s_xor_b64 s[10:11], exec, s[10:11]
	s_cbranch_execz .LBB0_1385
	s_waitcnt lgkmcnt(0)
	s_add_u32 s16, s84, 0x33500
	s_addc_u32 s17, s85, 0
	v_mov_b32_e32 v2, 0
	global_load_dword v2, v2, s[16:17] sc1
	s_waitcnt vmcnt(0)
	v_cmp_eq_u32_e32 vcc, v2, v3
	s_and_saveexec_b64 s[12:13], vcc
	s_cbranch_execz .LBB0_1384
	s_add_u32 s14, s84, 0x30200
	s_addc_u32 s15, s85, 0
	s_mov_b32 s28, 1
	s_mov_b64 s[18:19], 0
	v_mov_b32_e32 v2, 0
	s_branch .LBB0_1375

; __device__ __forceinline__ unsigned xb_ld(unsigned* p)              { return __hip_atomic_load(p, __ATOMIC_RELAXED, __HIP_MEMORY_SCOPE_AGENT); }
; __device__ __forceinline__ unsigned xb_add(unsigned* p, unsigned v) { return __hip_atomic_fetch_add(p, v, __ATOMIC_RELAXED, __HIP_MEMORY_SCOPE_AGENT); }
; #define XB_SPIN(cond, bar) do { unsigned _sp = 0; while (cond) { __builtin_amdgcn_s_sleep(1); \
;     if ((++_sp & 255u) == 0u) { if (xb_ld(&(bar)[XB_TMO])) break; if (_sp > XB_SPIN_CAP) { atomicAdd(&(bar)[XB_TMO], 1u); break; } } } } while (0)
; __device__ __forceinline__ void xcd_barrier(const XcdBarrier& b) {
;     ...
;         const unsigned old = xb_add(&bar[XB_XSUB(b.x)], 1u);
;         const unsigned gen = old / nloc;
;         if (old + 1u == (gen + 1u) * nloc) {
;             __builtin_amdgcn_fence(__ATOMIC_RELEASE, "agent");
;             asm volatile("s_waitcnt vmcnt(0)" ::: "memory");
;             const unsigned og = xb_add(&bar[XB_TOP], 1u);
;             const unsigned tg = og / nx;
;             if (og + 1u == (tg + 1u) * nx) xb_add(&bar[XB_TOPGEN], 1u);
;             else XB_SPIN(xb_ld(&bar[XB_TOPGEN]) == tg, bar);
;             __builtin_amdgcn_fence(__ATOMIC_ACQUIRE, "agent");
;             xb_add(&bar[XB_XGEN(b.x)], 1u);
;             asm volatile("s_waitcnt vmcnt(0)" ::: "memory");
;         } else {
;             XB_SPIN(xb_ld(&bar[XB_XGEN(b.x)]) == gen, bar);
.LBB0_1462:
	v_readlane_b32 s6, v254, 16
	s_lshl_b32 s6, s6, 8
	v_readlane_b32 s8, v254, 12
	v_readlane_b32 s9, v254, 13
	s_add_u32 s6, s8, s6
	s_addc_u32 s7, s9, 0
	v_mov_b32_e32 v3, 0x1000
	v_mov_b32_e32 v5, 1
	global_atomic_add v5, v3, v5, s[6:7] offset:1024 sc0
	v_cvt_f32_u32_e32 v3, v4
	v_sub_u32_e32 v6, 0, v4
	v_rcp_iflag_f32_e32 v3, v3
	s_nop 0
	v_mul_f32_e32 v3, 0x4f7ffffe, v3
	v_cvt_u32_f32_e32 v3, v3
	v_mul_lo_u32 v6, v6, v3
	v_mul_hi_u32 v6, v3, v6
	v_add_u32_e32 v3, v3, v6
	s_waitcnt vmcnt(0)
	v_mul_hi_u32 v3, v5, v3
	v_mul_lo_u32 v6, v3, v4
	v_sub_u32_e32 v6, v5, v6
	v_add_u32_e32 v7, 1, v3
	v_cmp_ge_u32_e32 vcc, v6, v4
	v_add_u32_e32 v5, 1, v5
	s_nop 0
	v_cndmask_b32_e32 v3, v3, v7, vcc
	v_sub_u32_e32 v7, v6, v4
	v_cndmask_b32_e32 v6, v6, v7, vcc
	v_add_u32_e32 v7, 1, v3
	v_cmp_ge_u32_e32 vcc, v6, v4
	s_nop 1
	v_cndmask_b32_e32 v3, v3, v7, vcc
	v_mul_lo_u32 v6, v4, v3
	v_add_u32_e32 v4, v6, v4
	v_cmp_ne_u32_e32 vcc, v5, v4
	s_and_saveexec_b64 s[8:9], vcc
	s_xor_b64 s[8:9], exec, s[8:9]
	s_cbranch_execz .LBB0_1476
	s_waitcnt lgkmcnt(0)
	s_add_u32 s14, s84, 0x33500
	s_addc_u32 s15, s85, 0
	v_mov_b32_e32 v2, 0
	global_load_dword v2, v2, s[14:15] sc1
	s_waitcnt vmcnt(0)
	v_cmp_eq_u32_e32 vcc, v2, v3
	s_and_saveexec_b64 s[10:11], vcc
	s_cbranch_execz .LBB0_1475
	s_add_u32 s12, s84, 0x30200
	s_addc_u32 s13, s85, 0
	s_mov_b32 s26, 1
	s_mov_b64 s[16:17], 0
	v_mov_b32_e32 v2, 0
	s_branch .LBB0_1466

; __device__ __forceinline__ unsigned xb_ld(unsigned* p)              { return __hip_atomic_load(p, __ATOMIC_RELAXED, __HIP_MEMORY_SCOPE_AGENT); }
; __device__ __forceinline__ unsigned xb_add(unsigned* p, unsigned v) { return __hip_atomic_fetch_add(p, v, __ATOMIC_RELAXED, __HIP_MEMORY_SCOPE_AGENT); }
; #define XB_SPIN(cond, bar) do { unsigned _sp = 0; while (cond) { __builtin_amdgcn_s_sleep(1); \
;     if ((++_sp & 255u) == 0u) { if (xb_ld(&(bar)[XB_TMO])) break; if (_sp > XB_SPIN_CAP) { atomicAdd(&(bar)[XB_TMO], 1u); break; } } } } while (0)
; __device__ __forceinline__ void xcd_barrier(const XcdBarrier& b) {
;     ...
;         const unsigned old = xb_add(&bar[XB_XSUB(b.x)], 1u);
;         const unsigned gen = old / nloc;
;         if (old + 1u == (gen + 1u) * nloc) {
;             __builtin_amdgcn_fence(__ATOMIC_RELEASE, "agent");
;             asm volatile("s_waitcnt vmcnt(0)" ::: "memory");
;             const unsigned og = xb_add(&bar[XB_TOP], 1u);
;             const unsigned tg = og / nx;
;             if (og + 1u == (tg + 1u) * nx) xb_add(&bar[XB_TOPGEN], 1u);
;             else XB_SPIN(xb_ld(&bar[XB_TOPGEN]) == tg, bar);
;             __builtin_amdgcn_fence(__ATOMIC_ACQUIRE, "agent");
;             xb_add(&bar[XB_XGEN(b.x)], 1u);
;             asm volatile("s_waitcnt vmcnt(0)" ::: "memory");
;         } else {
;             XB_SPIN(xb_ld(&bar[XB_XGEN(b.x)]) == gen, bar);
.LBB0_1963:
	v_readlane_b32 s2, v254, 16
	s_lshl_b32 s2, s2, 8
	v_readlane_b32 s4, v254, 12
	v_readlane_b32 s5, v254, 13
	s_add_u32 s2, s4, s2
	s_addc_u32 s3, s5, 0
	v_mov_b32_e32 v3, 0x1000
	v_mov_b32_e32 v5, 1
	global_atomic_add v5, v3, v5, s[2:3] offset:1024 sc0
	v_cvt_f32_u32_e32 v3, v4
	v_sub_u32_e32 v6, 0, v4
	v_rcp_iflag_f32_e32 v3, v3
	s_nop 0
	v_mul_f32_e32 v3, 0x4f7ffffe, v3
	v_cvt_u32_f32_e32 v3, v3
	v_mul_lo_u32 v6, v6, v3
	v_mul_hi_u32 v6, v3, v6
	v_add_u32_e32 v3, v3, v6
	s_waitcnt vmcnt(0)
	v_mul_hi_u32 v3, v5, v3
	v_mul_lo_u32 v6, v3, v4
	v_sub_u32_e32 v6, v5, v6
	v_add_u32_e32 v7, 1, v3
	v_cmp_ge_u32_e32 vcc, v6, v4
	v_add_u32_e32 v5, 1, v5
	s_nop 0
	v_cndmask_b32_e32 v3, v3, v7, vcc
	v_sub_u32_e32 v7, v6, v4
	v_cndmask_b32_e32 v6, v6, v7, vcc
	v_add_u32_e32 v7, 1, v3
	v_cmp_ge_u32_e32 vcc, v6, v4
	s_nop 1
	v_cndmask_b32_e32 v3, v3, v7, vcc
	v_mul_lo_u32 v6, v4, v3
	v_add_u32_e32 v4, v6, v4
	v_cmp_ne_u32_e32 vcc, v5, v4
	s_and_saveexec_b64 s[4:5], vcc
	s_xor_b64 s[4:5], exec, s[4:5]
	s_cbranch_execz .LBB0_1977
	s_waitcnt lgkmcnt(0)
	s_add_u32 s10, s84, 0x33500
	s_addc_u32 s11, s85, 0
	v_mov_b32_e32 v2, 0
	global_load_dword v2, v2, s[10:11] sc1
	s_waitcnt vmcnt(0)
	v_cmp_eq_u32_e32 vcc, v2, v3
	s_and_saveexec_b64 s[6:7], vcc
	s_cbranch_execz .LBB0_1976
	s_add_u32 s8, s84, 0x30200
	s_addc_u32 s9, s85, 0
	s_mov_b32 s22, 1
	s_mov_b64 s[12:13], 0
	v_mov_b32_e32 v2, 0
	s_branch .LBB0_1967
